# v30: attention K/V loop with MFMA-first head after the tile barrier (last 8 PV MFMAs deferred into the next iteration) and the loop counter/test moved in front of the barrier
# baseline (speedup 1.0000x reference)
.LBB0_747:
	s_and_b64 vcc, exec, s[10:11]
	s_cbranch_vccz .LBB0_751
	v_mov_b32_e32 v10, v232
	s_load_dwordx8 s[52:59], s[44:45], 0x60
	v_and_b32_e32 v181, 63, v10
	v_readlane_b32 s10, v255, 20
	v_mov_b32_e32 v3, v0
	s_load_dwordx2 s[42:43], s[44:45], 0xb0
	v_or_b32_e32 v2, s10, v181
	v_lshlrev_b64 v[2:3], 2, v[2:3]
	s_waitcnt lgkmcnt(0)
	v_lshl_add_u64 v[4:5], s[52:53], 0, v[2:3]
	global_load_dword v11, v[4:5], off
	v_lshl_add_u64 v[4:5], s[54:55], 0, v[2:3]
	global_load_dword v12, v[4:5], off
	v_lshl_add_u64 v[4:5], s[56:57], 0, v[2:3]
	v_lshl_add_u64 v[2:3], s[58:59], 0, v[2:3]
	global_load_dword v13, v[4:5], off
	global_load_dword v14, v[2:3], off
	s_add_i32 s6, s37, s48
	s_lshl_b32 s14, s36, 7
	s_lshl_b32 s30, s36, 8
	v_readlane_b32 s11, v255, 21
	s_add_u32 s10, s42, s47
	s_addc_u32 s11, s43, s46
	s_add_u32 s36, s10, s30
	s_addc_u32 s37, s11, 0
	s_lshl_b32 s10, s27, 10
	s_or_b32 s10, s14, s10
	s_mul_hi_i32 s11, s10, 0x2200
	s_mulk_i32 s10, 0x2200
	v_ashrrev_i32_e32 v50, 4, v10
	s_add_u32 s10, s42, s10
	v_ashrrev_i32_e32 v51, 31, v50
	v_and_b32_e32 v177, 15, v10
	s_addc_u32 s11, s43, s11
	v_lshlrev_b64 v[52:53], 11, v[50:51]
	s_add_u32 s40, s10, 0xe010000
	v_lshl_add_u64 v[2:3], s[36:37], 0, v[52:53]
	v_lshlrev_b32_e32 v124, 4, v177
	v_mov_b32_e32 v125, v0
	s_addc_u32 s41, s11, 0
	v_lshl_add_u64 v[2:3], v[2:3], 0, v[124:125]
	s_mov_b32 s15, 0x16810000
	v_mov_b64_e32 v[4:5], s[40:41]
	s_movk_i32 s35, 0x2200
	v_add_co_u32_e32 v6, vcc, s15, v2
	v_mad_i64_i32 v[4:5], s[36:37], v50, s35, v[4:5]
	s_nop 0
	v_addc_co_u32_e32 v7, vcc, 0, v3, vcc
	s_mov_b32 s15, 0x16820000
	v_lshl_add_u64 v[4:5], v[4:5], 0, v[124:125]
	global_load_dwordx4 v[18:21], v[6:7], off
	global_load_dwordx4 v[22:25], v[4:5], off
	v_add_co_u32_e32 v6, vcc, s15, v2
	s_mov_b32 s15, 0x44000
	s_nop 0
	v_addc_co_u32_e32 v7, vcc, 0, v3, vcc
	v_add_co_u32_e32 v8, vcc, s15, v4
	s_mov_b32 s15, 0x16830000
	s_nop 0
	v_addc_co_u32_e32 v9, vcc, 0, v5, vcc
	global_load_dwordx4 v[26:29], v[6:7], off
	global_load_dwordx4 v[30:33], v[8:9], off
	v_add_co_u32_e32 v6, vcc, s15, v2
	s_mov_b32 s15, 0x88000
	s_nop 0
	v_addc_co_u32_e32 v7, vcc, 0, v3, vcc
	v_add_co_u32_e32 v8, vcc, s15, v4
	s_mov_b32 s15, 0x16840000
	s_nop 0
	v_addc_co_u32_e32 v9, vcc, 0, v5, vcc
	v_add_co_u32_e32 v2, vcc, s15, v2
	s_mov_b32 s15, 0xcc000
	s_nop 0
	v_addc_co_u32_e32 v3, vcc, 0, v3, vcc
	v_add_co_u32_e32 v4, vcc, s15, v4
	global_load_dwordx4 v[34:37], v[6:7], off
	global_load_dwordx4 v[38:41], v[8:9], off
	v_addc_co_u32_e32 v5, vcc, 0, v5, vcc
	global_load_dwordx4 v[42:45], v[2:3], off
	global_load_dwordx4 v[46:49], v[4:5], off
	v_ashrrev_i32_e32 v4, 2, v10
	v_and_b32_e32 v4, 0xffffffe0, v4
	v_add_u32_e32 v180, s6, v4
	v_ashrrev_i32_e32 v182, 6, v10
	v_and_b32_e32 v179, 1, v182
	v_mov_b32_e32 v55, v0
	v_lshlrev_b32_e32 v54, 7, v179
	s_waitcnt vmcnt(10)
	v_mul_f32_e32 v2, v11, v12
	ds_bpermute_b32 v2, v1, v2
	v_and_b32_e32 v56, 48, v10
	v_mov_b32_e32 v57, v0
	s_waitcnt vmcnt(8)
	v_mul_f32_e32 v3, v13, v14
	ds_bpermute_b32 v3, v1, v3
	s_waitcnt lgkmcnt(1)
	v_fmac_f32_e32 v2, v11, v12
	ds_bpermute_b32 v5, v176, v2
	s_mov_b32 s6, 0x14610000
	s_mov_b64 s[36:37], 0x14610000
	s_waitcnt lgkmcnt(1)
	v_fmac_f32_e32 v3, v13, v14
	ds_bpermute_b32 v6, v176, v3
	s_waitcnt lgkmcnt(1)
	v_add_f32_e32 v4, v2, v5
	v_or_b32_e32 v2, v180, v177
	v_bfe_u32 v178, v10, 4, 2
	v_lshlrev_b32_e32 v51, 2, v50
	s_waitcnt lgkmcnt(0)
	v_add_f32_e32 v5, v3, v6
	ds_bpermute_b32 v6, v175, v4
	ds_bpermute_b32 v7, v175, v5
	v_ashrrev_i32_e32 v3, 31, v2
	v_lshlrev_b64 v[2:3], 11, v[2:3]
	v_lshl_add_u64 v[2:3], s[42:43], 0, v[2:3]
	s_waitcnt lgkmcnt(1)
	v_add_f32_e32 v4, v4, v6
	s_waitcnt lgkmcnt(0)
	v_add_f32_e32 v5, v5, v7
	ds_bpermute_b32 v6, v174, v4
	ds_bpermute_b32 v7, v174, v5
	v_lshl_add_u64 v[2:3], v[2:3], 0, s[30:31]
	v_lshl_add_u64 v[2:3], v[2:3], 0, v[54:55]
	v_lshrrev_b32_e32 v55, 1, v50
	s_waitcnt lgkmcnt(1)
	v_add_f32_e32 v132, v4, v6
	s_waitcnt lgkmcnt(0)
	v_add_f32_e32 v133, v5, v7
	v_lshl_add_u64 v[6:7], v[2:3], 0, v[56:57]
	v_add_co_u32_e32 v4, vcc, s6, v6
	s_mov_b32 s6, 0x14618000
	s_nop 0
	v_addc_co_u32_e32 v5, vcc, 0, v7, vcc
	v_lshl_add_u64 v[2:3], v[6:7], 0, s[36:37]
	v_add_co_u32_e32 v6, vcc, s6, v6
	global_load_dwordx4 v[10:13], v[4:5], off
	s_nop 0
	global_load_dwordx4 v[2:5], v[2:3], off offset:64
	v_addc_co_u32_e32 v7, vcc, 0, v7, vcc
	global_load_dwordx4 v[14:17], v[6:7], off
	s_nop 0
	global_load_dwordx4 v[6:9], v[6:7], off offset:64
	v_and_b32_e32 v51, 16, v51
	v_and_b32_e32 v55, 12, v55
	v_and_b32_e32 v57, 0xfffffe3, v50
	v_or3_b32 v51, v57, v51, v55
	s_movk_i32 s6, 0x110
	v_mul_lo_u32 v55, v50, s6
	v_mad_u64_u32 v[126:127], s[36:37], v51, s6, v[124:125]
	s_mov_b32 s6, 0x11000
	v_add3_u32 v127, v55, v124, s6
	v_add_u32_e32 v51, 0, v126
	v_add_u32_e32 v55, 0, v127
	s_waitcnt vmcnt(11)
	ds_write_b128 v51, v[18:21]
	s_waitcnt vmcnt(10)
	ds_write_b128 v55, v[22:25]
	s_waitcnt vmcnt(9)
	ds_write_b128 v51, v[26:29] offset:8704
	s_waitcnt vmcnt(8)
	ds_write_b128 v55, v[30:33] offset:8704
	s_waitcnt vmcnt(7)
	ds_write_b128 v51, v[34:37] offset:17408
	s_waitcnt vmcnt(6)
	ds_write_b128 v55, v[38:41] offset:17408
	s_waitcnt vmcnt(5)
	ds_write_b128 v51, v[42:45] offset:26112
	s_waitcnt vmcnt(4)
	ds_write_b128 v55, v[46:49] offset:26112
	s_add_i32 s6, 0, 0x11000
	v_mul_u32_u24_e32 v19, 0x110, v177
	v_add3_u32 v183, s6, v56, v19
	s_lshl_b32 s6, s26, 3
	s_and_b32 s6, s6, 0x700
	ds_bpermute_b32 v134, v173, v132
	ds_bpermute_b32 v135, v173, v133
	s_add_u32 s6, s42, s6
	v_add_u32_e32 v18, 0, v54
	s_addc_u32 s18, s43, 0
	v_add3_u32 v137, v18, v56, v19
	s_add_u32 s26, s6, s47
	v_mov_b64_e32 v[18:19], s[10:11]
	s_addc_u32 s27, s18, s46
	v_mad_i64_i32 v[130:131], s[10:11], v50, s35, v[18:19]
	v_mov_b32_e32 v18, 0
	s_mov_b32 s15, 0
	v_lshl_add_u64 v[128:129], s[26:27], 0, v[52:53]
	v_mov_b32_e32 v19, v18
	v_mov_b32_e32 v20, v18
	v_mov_b32_e32 v21, v18
	v_mov_b32_e32 v22, v18
	v_mov_b32_e32 v23, v18
	v_mov_b32_e32 v24, v18
	v_mov_b32_e32 v25, v18
	v_mov_b32_e32 v26, v18
	v_mov_b32_e32 v27, v18
	v_mov_b32_e32 v28, v18
	v_mov_b32_e32 v29, v18
	v_mov_b32_e32 v30, v18
	v_mov_b32_e32 v31, v18
	v_mov_b32_e32 v32, v18
	v_mov_b32_e32 v33, v18
	v_mov_b32_e32 v38, v18
	v_mov_b32_e32 v39, v18
	v_mov_b32_e32 v40, v18
	v_mov_b32_e32 v41, v18
	v_mov_b32_e32 v46, v18
	v_mov_b32_e32 v47, v18
	v_mov_b32_e32 v48, v18
	v_mov_b32_e32 v49, v18
	v_mov_b32_e32 v62, v18
	v_mov_b32_e32 v63, v18
	v_mov_b32_e32 v64, v18
	v_mov_b32_e32 v65, v18
	v_mov_b32_e32 v74, v18
	v_mov_b32_e32 v75, v18
	v_mov_b32_e32 v76, v18
	v_mov_b32_e32 v77, v18
	v_mov_b32_e32 v34, v18
	v_mov_b32_e32 v35, v18
	v_mov_b32_e32 v36, v18
	v_mov_b32_e32 v37, v18
	v_mov_b32_e32 v42, v18
	v_mov_b32_e32 v43, v18
	v_mov_b32_e32 v44, v18
	v_mov_b32_e32 v45, v18
	v_mov_b32_e32 v50, v18
	v_mov_b32_e32 v51, v18
	v_mov_b32_e32 v52, v18
	v_mov_b32_e32 v53, v18
	v_mov_b32_e32 v54, v18
	v_mov_b32_e32 v55, v18
	v_mov_b32_e32 v56, v18
	v_mov_b32_e32 v57, v18
	v_mov_b32_e32 v58, v18
	v_mov_b32_e32 v59, v18
	v_mov_b32_e32 v60, v18
	v_mov_b32_e32 v61, v18
	v_mov_b32_e32 v66, v18
	v_mov_b32_e32 v67, v18
	v_mov_b32_e32 v68, v18
	v_mov_b32_e32 v69, v18
	v_mov_b32_e32 v70, v18
	v_mov_b32_e32 v71, v18
	v_mov_b32_e32 v72, v18
	v_mov_b32_e32 v73, v18
	v_mov_b32_e32 v78, v18
	v_mov_b32_e32 v79, v18
	v_mov_b32_e32 v80, v18
	v_mov_b32_e32 v81, v18
	v_mov_b32_e32 v122, v18
	v_mov_b32_e32 v123, v18
	s_mov_b32 s11, 0xe054000
	s_mov_b32 s18, 0x16870000
	s_mov_b32 s26, 0xe098000
	s_mov_b32 s27, 0x16880000
	s_mov_b32 s30, 0xe0dc000
	s_mov_b64 s[36:37], 0x40000
	s_waitcnt lgkmcnt(0)
	s_barrier
	s_waitcnt vmcnt(0) lgkmcnt(0)
	v_writelane_b32 v175, s64, 0
	v_writelane_b32 v175, s65, 1
	v_writelane_b32 v175, s66, 2
	v_writelane_b32 v175, s67, 3
	v_writelane_b32 v175, s68, 4
	v_writelane_b32 v175, s69, 5
	v_writelane_b32 v175, s70, 6
	v_writelane_b32 v175, s71, 7
	v_writelane_b32 v175, s72, 8
	v_writelane_b32 v175, s73, 9
	v_writelane_b32 v175, s74, 10
	v_writelane_b32 v175, s75, 11
	v_writelane_b32 v175, s76, 12
	v_writelane_b32 v175, s77, 13
	v_writelane_b32 v175, s78, 14
	v_writelane_b32 v175, s79, 15
	v_lshl_add_u64 v[138:139], v[128:129], 0, v[124:125]
	v_lshl_add_u64 v[140:141], v[130:131], 0, v[124:125]
	s_nop 1
	v_readfirstlane_b32 s64, v138
	v_readfirstlane_b32 s65, v139
	v_readfirstlane_b32 s72, v140
	v_readfirstlane_b32 s73, v141
	s_nop 3
	v_subrev_u32_e32 v124, s64, v138
	v_subrev_u32_e32 v125, s72, v140
	s_add_u32 s66, s64, s97
	s_addc_u32 s67, s65, 0
	s_add_u32 s68, s64, s18
	s_addc_u32 s69, s65, 0
	s_add_u32 s70, s64, s27
	s_addc_u32 s71, s65, 0
	s_add_u32 s64, s64, s96
	s_addc_u32 s65, s65, 0
	s_add_u32 s74, s72, s11
	s_addc_u32 s75, s73, 0
	s_add_u32 s74, s74, 0x100
	s_addc_u32 s75, s75, 0
	s_add_u32 s76, s72, s26
	s_addc_u32 s77, s73, 0
	s_add_u32 s76, s76, 0x100
	s_addc_u32 s77, s77, 0
	s_add_u32 s78, s72, s30
	s_addc_u32 s79, s73, 0
	s_add_u32 s78, s78, 0x100
	s_addc_u32 s79, s79, 0
	s_add_u32 s72, s72, s91
	s_addc_u32 s73, s73, 0
	s_add_u32 s72, s72, 0x100
	s_addc_u32 s73, s73, 0
	s_mov_b32 s15, 0
	s_nop 4
	s_and_b32 s10, s15, 1
	s_mul_i32 s6, s10, 0x8800
	v_add_u32_e32 v136, s6, v137
	v_add_u32_e32 v170, s6, v183
	s_sub_u32 s10, 0x8800, s6
	ds_read_b128 v[98:101], v136 offset:0
	ds_read_b128 v[102:105], v136 offset:64
	ds_read_b128 v[106:109], v136 offset:4352
	ds_read_b128 v[110:113], v136 offset:4416
	v_add_u32_e32 v171, s10, v126
	v_add_u32_e32 v173, s10, v127
	global_load_dwordx4 v[82:85], v124, s[64:65]
	global_load_dwordx4 v[86:89], v124, s[66:67]
	global_load_dwordx4 v[90:93], v124, s[68:69]
	global_load_dwordx4 v[94:97], v124, s[70:71]
	v_add_u32_e32 v124, s36, v124
	s_branch .Lattn_after_def
.Lattn_nf_loop:
	v_mfma_f32_16x16x32_bf16 v[54:57], v[138:141], v[184:187], v[54:57]
	v_mfma_f32_16x16x32_bf16 v[30:33], v[138:141], v[128:131], v[30:33]
	s_and_b32 s10, s15, 1
	s_mul_i32 s6, s10, 0x8800
	v_add_u32_e32 v136, s6, v137
	v_add_u32_e32 v170, s6, v183
	s_sub_u32 s10, 0x8800, s6
	ds_read_b128 v[98:101], v136 offset:0
	ds_read_b128 v[102:105], v136 offset:64
	v_mfma_f32_16x16x32_bf16 v[50:53], v[142:145], v[184:187], v[50:53]
	v_mfma_f32_16x16x32_bf16 v[26:29], v[142:145], v[128:131], v[26:29]
	ds_read_b128 v[106:109], v136 offset:4352
	ds_read_b128 v[110:113], v136 offset:4416
	v_add_u32_e32 v171, s10, v126
	v_add_u32_e32 v173, s10, v127
	v_mfma_f32_16x16x32_bf16 v[42:45], v[146:149], v[184:187], v[42:45]
	v_mfma_f32_16x16x32_bf16 v[22:25], v[146:149], v[128:131], v[22:25]
	global_load_dwordx4 v[82:85], v124, s[64:65]
	global_load_dwordx4 v[86:89], v124, s[66:67]
	global_load_dwordx4 v[90:93], v124, s[68:69]
	global_load_dwordx4 v[94:97], v124, s[70:71]
	v_add_u32_e32 v124, s36, v124
	v_mfma_f32_16x16x32_bf16 v[34:37], v[150:153], v[184:187], v[34:37]
	v_mfma_f32_16x16x32_bf16 v[18:21], v[150:153], v[128:131], v[18:21]
.Lattn_after_def:
	s_waitcnt lgkmcnt(3)
	v_mfma_f32_16x16x32_bf16 v[138:141], v[98:101], v[10:13], 0
	v_mfma_f32_16x16x32_bf16 v[142:145], v[98:101], v[14:17], 0
	s_waitcnt lgkmcnt(2)
	v_mfma_f32_16x16x32_bf16 v[138:141], v[102:105], v[2:5], v[138:141]
	v_mfma_f32_16x16x32_bf16 v[142:145], v[102:105], v[6:9], v[142:145]
	ds_read_b128 v[98:101], v136 offset:8704
	ds_read_b128 v[102:105], v136 offset:8768
	s_waitcnt lgkmcnt(3)
	v_mfma_f32_16x16x32_bf16 v[146:149], v[106:109], v[10:13], 0
	v_mfma_f32_16x16x32_bf16 v[150:153], v[106:109], v[14:17], 0
	s_waitcnt lgkmcnt(2)
	v_mfma_f32_16x16x32_bf16 v[146:149], v[110:113], v[2:5], v[146:149]
	v_mfma_f32_16x16x32_bf16 v[150:153], v[110:113], v[6:9], v[150:153]
	ds_read_b128 v[106:109], v136 offset:13056
	ds_read_b128 v[110:113], v136 offset:13120
	v_exp_f32_e32 v138, v138
	v_exp_f32_e32 v139, v139
	v_exp_f32_e32 v140, v140
	v_exp_f32_e32 v141, v141
	v_exp_f32_e32 v142, v142
	v_exp_f32_e32 v143, v143
	v_exp_f32_e32 v144, v144
	v_exp_f32_e32 v145, v145
	v_add_f32_e32 v123, v138, v123
	v_add_f32_e32 v122, v142, v122
	v_add_f32_e32 v123, v139, v123
	v_add_f32_e32 v122, v143, v122
	v_add_f32_e32 v123, v140, v123
	v_add_f32_e32 v122, v144, v122
	v_add_f32_e32 v123, v141, v123
	v_add_f32_e32 v122, v145, v122
	s_waitcnt lgkmcnt(3)
	v_mfma_f32_16x16x32_bf16 v[154:157], v[98:101], v[10:13], 0
	v_exp_f32_e32 v146, v146
	v_exp_f32_e32 v147, v147
	v_mfma_f32_16x16x32_bf16 v[158:161], v[98:101], v[14:17], 0
	v_exp_f32_e32 v148, v148
	v_exp_f32_e32 v149, v149
	s_waitcnt lgkmcnt(2)
	v_mfma_f32_16x16x32_bf16 v[154:157], v[102:105], v[2:5], v[154:157]
	v_exp_f32_e32 v150, v150
	v_exp_f32_e32 v151, v151
	v_mfma_f32_16x16x32_bf16 v[158:161], v[102:105], v[6:9], v[158:161]
	v_exp_f32_e32 v152, v152
	v_exp_f32_e32 v153, v153
	v_cvt_pk_bf16_f32 v114, v138, v139
	v_cvt_pk_bf16_f32 v115, v140, v141
	v_cvt_pk_bf16_f32 v118, v142, v143
	v_cvt_pk_bf16_f32 v119, v144, v145
	ds_read_b128 v[138:141], v170 offset:0
	ds_read_b128 v[142:145], v170 offset:4352
	s_waitcnt lgkmcnt(3)
	v_mfma_f32_16x16x32_bf16 v[162:165], v[106:109], v[10:13], 0
	v_add_f32_e32 v123, v146, v123
	v_add_f32_e32 v122, v150, v122
	v_add_f32_e32 v123, v147, v123
	v_mfma_f32_16x16x32_bf16 v[166:169], v[106:109], v[14:17], 0
	v_add_f32_e32 v122, v151, v122
	v_add_f32_e32 v123, v148, v123
	v_add_f32_e32 v122, v152, v122
	s_waitcnt lgkmcnt(2)
	v_mfma_f32_16x16x32_bf16 v[162:165], v[110:113], v[2:5], v[162:165]
	v_add_f32_e32 v123, v149, v123
	v_add_f32_e32 v122, v153, v122
	v_cvt_pk_bf16_f32 v116, v146, v147
	v_cvt_pk_bf16_f32 v117, v148, v149
	v_mfma_f32_16x16x32_bf16 v[166:169], v[110:113], v[6:9], v[166:169]
	v_cvt_pk_bf16_f32 v120, v150, v151
	v_cvt_pk_bf16_f32 v121, v152, v153
	ds_read_b128 v[146:149], v170 offset:8704
	ds_read_b128 v[150:153], v170 offset:13056
	ds_read_b128 v[98:101], v170 offset:17408
	ds_read_b128 v[102:105], v170 offset:21760
	ds_read_b128 v[106:109], v170 offset:26112
	ds_read_b128 v[110:113], v170 offset:30464
	v_exp_f32_e32 v154, v154
	v_exp_f32_e32 v155, v155
	v_exp_f32_e32 v156, v156
	v_exp_f32_e32 v157, v157
	v_exp_f32_e32 v158, v158
	v_exp_f32_e32 v159, v159
	v_exp_f32_e32 v160, v160
	v_exp_f32_e32 v161, v161
	s_waitcnt lgkmcnt(7)
	v_mfma_f32_16x16x32_bf16 v[78:81], v[138:141], v[114:117], v[78:81]
	v_mfma_f32_16x16x32_bf16 v[74:77], v[138:141], v[118:121], v[74:77]
	v_exp_f32_e32 v162, v162
	v_exp_f32_e32 v163, v163
	v_exp_f32_e32 v164, v164
	v_exp_f32_e32 v165, v165
	s_waitcnt lgkmcnt(6)
	v_mfma_f32_16x16x32_bf16 v[70:73], v[142:145], v[114:117], v[70:73]
	v_mfma_f32_16x16x32_bf16 v[62:65], v[142:145], v[118:121], v[62:65]
	v_exp_f32_e32 v166, v166
	v_exp_f32_e32 v167, v167
	v_exp_f32_e32 v168, v168
	v_exp_f32_e32 v169, v169
	s_waitcnt lgkmcnt(5)
	v_mfma_f32_16x16x32_bf16 v[66:69], v[146:149], v[114:117], v[66:69]
	v_mfma_f32_16x16x32_bf16 v[46:49], v[146:149], v[118:121], v[46:49]
	v_add_f32_e32 v123, v154, v123
	v_add_f32_e32 v122, v158, v122
	v_add_f32_e32 v123, v155, v123
	v_add_f32_e32 v122, v159, v122
	v_add_f32_e32 v123, v156, v123
	v_add_f32_e32 v122, v160, v122
	v_add_f32_e32 v123, v157, v123
	v_add_f32_e32 v122, v161, v122
	s_waitcnt lgkmcnt(4)
	v_mfma_f32_16x16x32_bf16 v[58:61], v[150:153], v[114:117], v[58:61]
	v_mfma_f32_16x16x32_bf16 v[38:41], v[150:153], v[118:121], v[38:41]
	ds_read_b128 v[138:141], v170 offset:17472
	ds_read_b128 v[142:145], v170 offset:21824
	ds_read_b128 v[146:149], v170 offset:26176
	ds_read_b128 v[150:153], v170 offset:30528
	v_cvt_pk_bf16_f32 v184, v154, v155
	v_cvt_pk_bf16_f32 v185, v156, v157
	v_cvt_pk_bf16_f32 v128, v158, v159
	v_cvt_pk_bf16_f32 v129, v160, v161
	s_waitcnt lgkmcnt(7)
	v_mfma_f32_16x16x32_bf16 v[54:57], v[98:101], v[114:117], v[54:57]
	v_mfma_f32_16x16x32_bf16 v[30:33], v[98:101], v[118:121], v[30:33]
	v_add_f32_e32 v123, v162, v123
	v_add_f32_e32 v122, v166, v122
	v_add_f32_e32 v123, v163, v123
	v_add_f32_e32 v122, v167, v122
	v_add_f32_e32 v123, v164, v123
	v_add_f32_e32 v122, v168, v122
	v_add_f32_e32 v123, v165, v123
	v_add_f32_e32 v122, v169, v122
	s_waitcnt lgkmcnt(6)
	v_mfma_f32_16x16x32_bf16 v[50:53], v[102:105], v[114:117], v[50:53]
	v_mfma_f32_16x16x32_bf16 v[26:29], v[102:105], v[118:121], v[26:29]
	v_cvt_pk_bf16_f32 v186, v162, v163
	v_cvt_pk_bf16_f32 v187, v164, v165
	v_cvt_pk_bf16_f32 v130, v166, v167
	v_cvt_pk_bf16_f32 v131, v168, v169
	ds_read_b128 v[154:157], v170 offset:64
	ds_read_b128 v[158:161], v170 offset:4416
	ds_read_b128 v[162:165], v170 offset:8768
	ds_read_b128 v[166:169], v170 offset:13120
	s_waitcnt lgkmcnt(9)
	v_mfma_f32_16x16x32_bf16 v[42:45], v[106:109], v[114:117], v[42:45]
	v_mfma_f32_16x16x32_bf16 v[22:25], v[106:109], v[118:121], v[22:25]
	s_waitcnt lgkmcnt(8)
	v_mfma_f32_16x16x32_bf16 v[34:37], v[110:113], v[114:117], v[34:37]
	v_mfma_f32_16x16x32_bf16 v[18:21], v[110:113], v[118:121], v[18:21]
	ds_read_b128 v[98:101], v136 offset:17408
	ds_read_b128 v[102:105], v136 offset:17472
	ds_read_b128 v[106:109], v136 offset:21760
	ds_read_b128 v[110:113], v136 offset:21824
	s_waitcnt lgkmcnt(7)
	v_mfma_f32_16x16x32_bf16 v[78:81], v[154:157], v[184:187], v[78:81]
	v_mfma_f32_16x16x32_bf16 v[74:77], v[154:157], v[128:131], v[74:77]
	s_waitcnt lgkmcnt(6)
	v_mfma_f32_16x16x32_bf16 v[70:73], v[158:161], v[184:187], v[70:73]
	v_mfma_f32_16x16x32_bf16 v[62:65], v[158:161], v[128:131], v[62:65]
	s_waitcnt vmcnt(3)
	ds_write_b128 v171, v[82:85] offset:0
	s_waitcnt vmcnt(2)
	ds_write_b128 v171, v[86:89] offset:8704
	s_waitcnt vmcnt(1)
	ds_write_b128 v171, v[90:93] offset:17408
	s_waitcnt vmcnt(0)
	ds_write_b128 v171, v[94:97] offset:26112
	s_waitcnt lgkmcnt(9)
	v_mfma_f32_16x16x32_bf16 v[66:69], v[162:165], v[184:187], v[66:69]
	v_mfma_f32_16x16x32_bf16 v[46:49], v[162:165], v[128:131], v[46:49]
	s_waitcnt lgkmcnt(8)
	v_mfma_f32_16x16x32_bf16 v[58:61], v[166:169], v[184:187], v[58:61]
	v_mfma_f32_16x16x32_bf16 v[38:41], v[166:169], v[128:131], v[38:41]
	global_load_dwordx4 v[82:85], v125, s[72:73]
	global_load_dwordx4 v[86:89], v125, s[74:75]
	global_load_dwordx4 v[90:93], v125, s[76:77]
	global_load_dwordx4 v[94:97], v125, s[78:79]
	v_add_u32_e32 v125, s38, v125
	v_mfma_f32_16x16x32_bf16 v[54:57], v[138:141], v[184:187], v[54:57]
	v_mfma_f32_16x16x32_bf16 v[30:33], v[138:141], v[128:131], v[30:33]
	v_mfma_f32_16x16x32_bf16 v[50:53], v[142:145], v[184:187], v[50:53]
	v_mfma_f32_16x16x32_bf16 v[26:29], v[142:145], v[128:131], v[26:29]
	v_mfma_f32_16x16x32_bf16 v[42:45], v[146:149], v[184:187], v[42:45]
	v_mfma_f32_16x16x32_bf16 v[22:25], v[146:149], v[128:131], v[22:25]
	v_mfma_f32_16x16x32_bf16 v[34:37], v[150:153], v[184:187], v[34:37]
	v_mfma_f32_16x16x32_bf16 v[18:21], v[150:153], v[128:131], v[18:21]
	s_waitcnt lgkmcnt(7)
	v_mfma_f32_16x16x32_bf16 v[138:141], v[98:101], v[10:13], 0
	v_mfma_f32_16x16x32_bf16 v[142:145], v[98:101], v[14:17], 0
	s_waitcnt lgkmcnt(6)
	v_mfma_f32_16x16x32_bf16 v[138:141], v[102:105], v[2:5], v[138:141]
	v_mfma_f32_16x16x32_bf16 v[142:145], v[102:105], v[6:9], v[142:145]
	ds_read_b128 v[98:101], v136 offset:26112
	ds_read_b128 v[102:105], v136 offset:26176
	s_waitcnt lgkmcnt(7)
	v_mfma_f32_16x16x32_bf16 v[146:149], v[106:109], v[10:13], 0
	v_mfma_f32_16x16x32_bf16 v[150:153], v[106:109], v[14:17], 0
	s_waitcnt lgkmcnt(6)
	v_mfma_f32_16x16x32_bf16 v[146:149], v[110:113], v[2:5], v[146:149]
	v_mfma_f32_16x16x32_bf16 v[150:153], v[110:113], v[6:9], v[150:153]
	ds_read_b128 v[106:109], v136 offset:30464
	ds_read_b128 v[110:113], v136 offset:30528
	v_exp_f32_e32 v138, v138
	v_exp_f32_e32 v139, v139
	v_exp_f32_e32 v140, v140
	v_exp_f32_e32 v141, v141
	v_exp_f32_e32 v142, v142
	v_exp_f32_e32 v143, v143
	v_exp_f32_e32 v144, v144
	v_exp_f32_e32 v145, v145
	v_add_f32_e32 v123, v138, v123
	v_add_f32_e32 v122, v142, v122
	v_add_f32_e32 v123, v139, v123
	v_add_f32_e32 v122, v143, v122
	v_add_f32_e32 v123, v140, v123
	v_add_f32_e32 v122, v144, v122
	v_add_f32_e32 v123, v141, v123
	v_add_f32_e32 v122, v145, v122
	s_waitcnt lgkmcnt(3)
	v_mfma_f32_16x16x32_bf16 v[154:157], v[98:101], v[10:13], 0
	v_exp_f32_e32 v146, v146
	v_exp_f32_e32 v147, v147
	v_mfma_f32_16x16x32_bf16 v[158:161], v[98:101], v[14:17], 0
	v_exp_f32_e32 v148, v148
	v_exp_f32_e32 v149, v149
	s_waitcnt lgkmcnt(2)
	v_mfma_f32_16x16x32_bf16 v[154:157], v[102:105], v[2:5], v[154:157]
	v_exp_f32_e32 v150, v150
	v_exp_f32_e32 v151, v151
	v_mfma_f32_16x16x32_bf16 v[158:161], v[102:105], v[6:9], v[158:161]
	v_exp_f32_e32 v152, v152
	v_exp_f32_e32 v153, v153
	v_cvt_pk_bf16_f32 v114, v138, v139
	v_cvt_pk_bf16_f32 v115, v140, v141
	v_cvt_pk_bf16_f32 v118, v142, v143
	v_cvt_pk_bf16_f32 v119, v144, v145
	ds_read_b128 v[138:141], v170 offset:128
	ds_read_b128 v[142:145], v170 offset:4480
	s_waitcnt lgkmcnt(3)
	v_mfma_f32_16x16x32_bf16 v[162:165], v[106:109], v[10:13], 0
	v_add_f32_e32 v123, v146, v123
	v_add_f32_e32 v122, v150, v122
	v_add_f32_e32 v123, v147, v123
	v_mfma_f32_16x16x32_bf16 v[166:169], v[106:109], v[14:17], 0
	v_add_f32_e32 v122, v151, v122
	v_add_f32_e32 v123, v148, v123
	v_add_f32_e32 v122, v152, v122
	s_waitcnt lgkmcnt(2)
	v_mfma_f32_16x16x32_bf16 v[162:165], v[110:113], v[2:5], v[162:165]
	v_add_f32_e32 v123, v149, v123
	v_add_f32_e32 v122, v153, v122
	v_cvt_pk_bf16_f32 v116, v146, v147
	v_cvt_pk_bf16_f32 v117, v148, v149
	v_mfma_f32_16x16x32_bf16 v[166:169], v[110:113], v[6:9], v[166:169]
	v_cvt_pk_bf16_f32 v120, v150, v151
	v_cvt_pk_bf16_f32 v121, v152, v153
	ds_read_b128 v[146:149], v170 offset:8832
	ds_read_b128 v[150:153], v170 offset:13184
	ds_read_b128 v[98:101], v170 offset:17536
	ds_read_b128 v[102:105], v170 offset:21888
	ds_read_b128 v[106:109], v170 offset:26240
	ds_read_b128 v[110:113], v170 offset:30592
	v_exp_f32_e32 v154, v154
	v_exp_f32_e32 v155, v155
	v_exp_f32_e32 v156, v156
	v_exp_f32_e32 v157, v157
	v_exp_f32_e32 v158, v158
	v_exp_f32_e32 v159, v159
	v_exp_f32_e32 v160, v160
	v_exp_f32_e32 v161, v161
	s_waitcnt lgkmcnt(7)
	v_mfma_f32_16x16x32_bf16 v[78:81], v[138:141], v[114:117], v[78:81]
	v_mfma_f32_16x16x32_bf16 v[74:77], v[138:141], v[118:121], v[74:77]
	v_exp_f32_e32 v162, v162
	v_exp_f32_e32 v163, v163
	v_exp_f32_e32 v164, v164
	v_exp_f32_e32 v165, v165
	s_waitcnt lgkmcnt(6)
	v_mfma_f32_16x16x32_bf16 v[70:73], v[142:145], v[114:117], v[70:73]
	v_mfma_f32_16x16x32_bf16 v[62:65], v[142:145], v[118:121], v[62:65]
	v_exp_f32_e32 v166, v166
	v_exp_f32_e32 v167, v167
	v_exp_f32_e32 v168, v168
	v_exp_f32_e32 v169, v169
	s_waitcnt lgkmcnt(5)
	v_mfma_f32_16x16x32_bf16 v[66:69], v[146:149], v[114:117], v[66:69]
	v_mfma_f32_16x16x32_bf16 v[46:49], v[146:149], v[118:121], v[46:49]
	v_add_f32_e32 v123, v154, v123
	v_add_f32_e32 v122, v158, v122
	v_add_f32_e32 v123, v155, v123
	v_add_f32_e32 v122, v159, v122
	v_add_f32_e32 v123, v156, v123
	v_add_f32_e32 v122, v160, v122
	v_add_f32_e32 v123, v157, v123
	v_add_f32_e32 v122, v161, v122
	s_waitcnt lgkmcnt(4)
	v_mfma_f32_16x16x32_bf16 v[58:61], v[150:153], v[114:117], v[58:61]
	v_mfma_f32_16x16x32_bf16 v[38:41], v[150:153], v[118:121], v[38:41]
	ds_read_b128 v[138:141], v170 offset:17600
	ds_read_b128 v[142:145], v170 offset:21952
	ds_read_b128 v[146:149], v170 offset:26304
	ds_read_b128 v[150:153], v170 offset:30656
	v_cvt_pk_bf16_f32 v184, v154, v155
	v_cvt_pk_bf16_f32 v185, v156, v157
	v_cvt_pk_bf16_f32 v128, v158, v159
	v_cvt_pk_bf16_f32 v129, v160, v161
	s_waitcnt lgkmcnt(7)
	v_mfma_f32_16x16x32_bf16 v[54:57], v[98:101], v[114:117], v[54:57]
	v_mfma_f32_16x16x32_bf16 v[30:33], v[98:101], v[118:121], v[30:33]
	v_add_f32_e32 v123, v162, v123
	v_add_f32_e32 v122, v166, v122
	v_add_f32_e32 v123, v163, v123
	v_add_f32_e32 v122, v167, v122
	v_add_f32_e32 v123, v164, v123
	v_add_f32_e32 v122, v168, v122
	v_add_f32_e32 v123, v165, v123
	v_add_f32_e32 v122, v169, v122
	s_waitcnt lgkmcnt(6)
	v_mfma_f32_16x16x32_bf16 v[50:53], v[102:105], v[114:117], v[50:53]
	v_mfma_f32_16x16x32_bf16 v[26:29], v[102:105], v[118:121], v[26:29]
	v_cvt_pk_bf16_f32 v186, v162, v163
	v_cvt_pk_bf16_f32 v187, v164, v165
	v_cvt_pk_bf16_f32 v130, v166, v167
	v_cvt_pk_bf16_f32 v131, v168, v169
	ds_read_b128 v[154:157], v170 offset:192
	ds_read_b128 v[158:161], v170 offset:4544
	ds_read_b128 v[162:165], v170 offset:8896
	ds_read_b128 v[166:169], v170 offset:13248
	s_waitcnt lgkmcnt(9)
	v_mfma_f32_16x16x32_bf16 v[42:45], v[106:109], v[114:117], v[42:45]
	v_mfma_f32_16x16x32_bf16 v[22:25], v[106:109], v[118:121], v[22:25]
	s_waitcnt lgkmcnt(8)
	v_mfma_f32_16x16x32_bf16 v[34:37], v[110:113], v[114:117], v[34:37]
	v_mfma_f32_16x16x32_bf16 v[18:21], v[110:113], v[118:121], v[18:21]
	s_waitcnt lgkmcnt(3)
	v_mfma_f32_16x16x32_bf16 v[78:81], v[154:157], v[184:187], v[78:81]
	v_mfma_f32_16x16x32_bf16 v[74:77], v[154:157], v[128:131], v[74:77]
	s_waitcnt lgkmcnt(2)
	v_mfma_f32_16x16x32_bf16 v[70:73], v[158:161], v[184:187], v[70:73]
	v_mfma_f32_16x16x32_bf16 v[62:65], v[158:161], v[128:131], v[62:65]
	s_waitcnt lgkmcnt(1)
	v_mfma_f32_16x16x32_bf16 v[66:69], v[162:165], v[184:187], v[66:69]
	v_mfma_f32_16x16x32_bf16 v[46:49], v[162:165], v[128:131], v[46:49]
	s_waitcnt lgkmcnt(0)
	v_mfma_f32_16x16x32_bf16 v[58:61], v[166:169], v[184:187], v[58:61]
	v_mfma_f32_16x16x32_bf16 v[38:41], v[166:169], v[128:131], v[38:41]
	s_waitcnt vmcnt(3)
	ds_write_b128 v173, v[82:85] offset:0
	s_waitcnt vmcnt(2)
	ds_write_b128 v173, v[86:89] offset:8704
	s_waitcnt vmcnt(1)
	ds_write_b128 v173, v[90:93] offset:17408
	s_waitcnt vmcnt(0)
	ds_write_b128 v173, v[94:97] offset:26112
	s_waitcnt lgkmcnt(0)
	s_add_i32 s15, s15, 1
	s_cmp_eq_u32 s15, 33
	s_barrier
	s_cbranch_scc0 .Lattn_nf_loop
	v_mfma_f32_16x16x32_bf16 v[54:57], v[138:141], v[184:187], v[54:57]
	v_mfma_f32_16x16x32_bf16 v[30:33], v[138:141], v[128:131], v[30:33]
	v_mfma_f32_16x16x32_bf16 v[50:53], v[142:145], v[184:187], v[50:53]
	v_mfma_f32_16x16x32_bf16 v[26:29], v[142:145], v[128:131], v[26:29]
	v_mfma_f32_16x16x32_bf16 v[42:45], v[146:149], v[184:187], v[42:45]
	v_mfma_f32_16x16x32_bf16 v[22:25], v[146:149], v[128:131], v[22:25]
	v_mfma_f32_16x16x32_bf16 v[34:37], v[150:153], v[184:187], v[34:37]
	v_mfma_f32_16x16x32_bf16 v[18:21], v[150:153], v[128:131], v[18:21]
	v_readlane_b32 s64, v175, 0
	v_readlane_b32 s65, v175, 1
	v_readlane_b32 s66, v175, 2
	v_readlane_b32 s67, v175, 3
	v_readlane_b32 s68, v175, 4
	v_readlane_b32 s69, v175, 5
	v_readlane_b32 s70, v175, 6
	v_readlane_b32 s71, v175, 7
	v_readlane_b32 s72, v175, 8
	v_readlane_b32 s73, v175, 9
	v_readlane_b32 s74, v175, 10
	v_readlane_b32 s75, v175, 11
	v_readlane_b32 s76, v175, 12
	v_readlane_b32 s77, v175, 13
	v_readlane_b32 s78, v175, 14
	v_readlane_b32 s79, v175, 15
	s_nop 4
	ds_read_b128 v[82:85], v137 offset:34816
	ds_read_b128 v[90:93], v137 offset:34880
	v_add_f32_e32 v186, v132, v134
	v_add_f32_e32 v184, v133, v135
	ds_bpermute_b32 v187, v172, v186
	ds_bpermute_b32 v185, v172, v184
	s_mov_b32 s10, 0x3fb8aa3b
	s_mov_b32 s11, 0xc2ce8ed0
	s_mov_b32 s6, 0x42b17218
	s_waitcnt lgkmcnt(3)
	v_mfma_f32_16x16x32_bf16 v[86:89], v[82:85], v[10:13], 0
	v_cmp_eq_u32_e64 s[40:41], 0, v179
	s_lshl_b32 s30, s14, 1
	v_lshlrev_b32_e32 v196, 3, v178
	v_mov_b32_e32 v197, 0
	v_lshlrev_b32_e32 v198, 4, v179
	v_or3_b32 v198, v198, v177, v180
	v_ashrrev_i32_e32 v199, 31, v198
	v_lshlrev_b64 v[198:199], 11, v[198:199]
	s_mov_b64 s[100:101], 0x18a10000
	v_lshl_add_u64 v[198:199], s[42:43], 0, v[198:199]
	v_lshl_add_u64 v[198:199], v[198:199], 0, s[30:31]
	v_lshl_add_u64 v[198:199], v[198:199], 0, v[196:197]
	v_lshl_add_u64 v[198:199], v[198:199], 0, s[100:101]
	global_load_dwordx2 v[146:147], v[198:199], off
	global_load_dwordx2 v[148:149], v[198:199], off offset:32
	global_load_dwordx2 v[150:151], v[198:199], off offset:64
	global_load_dwordx2 v[152:153], v[198:199], off offset:96
	global_load_dwordx2 v[188:189], v[198:199], off offset:128
	global_load_dwordx2 v[190:191], v[198:199], off offset:160
	global_load_dwordx2 v[192:193], v[198:199], off offset:192
	global_load_dwordx2 v[194:195], v[198:199], off offset:224
	s_mov_b64 s[100:101], exec
	s_and_b64 exec, exec, s[4:5]
	s_cbranch_execz .Lpop_skip
	v_readlane_b32 s14, v255, 22
	v_readlane_b32 s15, v255, 23
	v_mov_b32_e32 v224, 1
	s_nop 4
	global_atomic_add v224, v0, v224, s[14:15] sc0
